# GEMM tiles (up-proj, in-proj): the trailing wave half's re-stagger barrier moved from behind the epilogue into the first K-loop iteration, behind its tile set-up and first fragment reads, which now ov
# baseline (speedup 1.0000x reference)
; #define PG8_STAGE(bufoff, gbase, voff) do { _Pragma("unroll") for (int _i = 0; _i < 2; ++_i) \
;         __builtin_amdgcn_global_load_lds((const unsigned*)((const char*)(gbase) + (voff)[_i]), (PG8_LAS unsigned*)(lds + (bufoff) + ldsw + _i * 8192), 16, 0, 0); } while (0)
; #define PG8_LDA(dst, b, h) do { _Pragma("unroll") for (int m = 0; m < 4; ++m) _Pragma("unroll") for (int k = 0; k < 2; ++k) dst[m][k] = *(const PG8_LAS bf16x8*)(lds + PG8_SA(b, h) + aoff + m * 2048 + k * 1024); } while (0)
; #define PG8_LDB(dst, b, h) do { _Pragma("unroll") for (int n = 0; n < 2; ++n) _Pragma("unroll") for (int k = 0; k < 2; ++k) dst[n][k] = *(const PG8_LAS bf16x8*)(lds + PG8_SB(b, h) + boff + n * 2048 + k * 1024); } while (0)
; #define PG8_MMA(ai, bj, At, Bt) do { __builtin_amdgcn_s_setprio(1); _Pragma("unroll") for (int m = 0; m < 4; ++m) _Pragma("unroll") for (int n = 0; n < 2; ++n) _Pragma("unroll") for (int k = 0; k < 2; ++k) \
;         acc[ai][bj][m][n] = __builtin_amdgcn_mfma_f32_16x16x32_bf16(Bt[n][k], At[m][k], acc[ai][bj][m][n], 0, 0, 0); __builtin_amdgcn_s_setprio(0); } while (0)
; #define PG8_WAIT_V(n) asm volatile("s_waitcnt vmcnt(" #n ")" ::: "memory")
; #define PG8_WAIT_L(n) asm volatile("s_waitcnt lgkmcnt(" #n ")" ::: "memory")
; template <class Epi, class Sched, bool ALIGN_EPI = false, bool SP2 = false>
; __device__ __forceinline__ void gemm_phase(PG8_LAS unsigned char* lds, const Gemm g, const Sched& S, const Epi& E) {
;     ...
;         const char* nA = has_next ? (const char*)g.A + (size_t)nxt.pm * tstep : cA; const char* nB = has_next ? (const char*)g.Bt + (size_t)nxt.pn * tstep : cB;
;         for (int t = 0; t < nt; t += 2) {
;             const bool last = (t == nt - 2);
;             const char* a1 = cA + (size_t)(t + 1) * kstep;
;             const char* a2 = last ? nA : cA + (size_t)(t + 2) * kstep; const char* b2 = last ? nB : cB + (size_t)(t + 2) * kstep;
;             const char* a3 = a2 + kstep; const char* b3 = b2 + kstep;
;             if (last && has_next) S.a_ready(nxt);
;             if constexpr (SP2) {
;             PG8_LDB(B0, 0, 0); PG8_LDB(B1, 0, 1); PG8_SCHED; PG8_LDA(At, 0, 0); PG8_STAGE(PG8_SA(1, 1), a1 + hstep, voffA);
;             PG8_WAIT_V(8); PG8_WAIT_L(0); PG8_BAR; PG8_MMA(0, 0, At, B0); PG8_MMA(0, 1, At, B1); PG8_BAR; PG8_SCHED;
;     ...
;         if constexpr (ALIGN_EPI) { if (wr == 1) PG8_BAR; }
.Lstg_done:
	s_ashr_i32 s27, s26, 31
	s_lshl_b64 s[12:13], s[26:27], 20
	s_add_u32 s94, s18, s12
	s_addc_u32 s95, s19, s13
	s_and_b64 s[12:13], s[46:47], exec
	s_cselect_b32 s27, s95, s69
	s_cselect_b32 s86, s94, s68
	s_ashr_i32 s17, s16, 31
	s_lshl_b64 s[12:13], s[16:17], 20
	v_readlane_b32 s14, v254, 38
	v_readlane_b32 s15, v254, 39
	s_add_u32 s14, s14, s12
	s_addc_u32 s15, s15, s13
	s_and_b64 s[12:13], s[46:47], exec
	s_cselect_b32 s17, s15, s11
	s_cselect_b32 s88, s14, s10
	s_add_u32 vcc_lo, s68, 0x80080
	s_addc_u32 vcc_hi, s69, 0
	s_add_u32 s21, s10, 0x100
	s_addc_u32 s12, s11, 0
	s_mov_b32 s13, -2
	v_add_u32_e32 v218, 0x10000, v194
	s_add_u32 s10, vcc_lo, 0xfff80080
	s_addc_u32 s11, vcc_hi, -1
	s_add_i32 s84, 0, 0x10000
	s_cmp_eq_u32 s13, 28
	s_cselect_b32 s69, s27, s11
	s_cselect_b32 s68, s86, s10
	s_cselect_b32 s11, s17, s12
	s_cselect_b32 s10, s88, s21
	s_add_i32 s93, 0, 0x14000
	ds_read_b128 v[114:117], v218
	ds_read_b128 v[118:121], v218 offset:1024
	ds_read_b128 v[130:133], v218 offset:2048
	ds_read_b128 v[138:141], v218 offset:3072
	ds_read_b128 v[146:149], v218 offset:16384
	ds_read_b128 v[156:159], v218 offset:17408
	ds_read_b128 v[160:163], v218 offset:18432
	ds_read_b128 v[164:167], v218 offset:19456
	s_add_i32 m0, s2, 0xc000
	ds_read_b128 v[168:171], v199
	ds_read_b128 v[172:175], v199 offset:1024
	ds_read_b128 v[176:179], v199 offset:2048
	ds_read_b128 v[180:183], v199 offset:3072
	ds_read_b128 v[184:187], v199 offset:4096
	ds_read_b128 v[188:191], v199 offset:5120
	ds_read_b128 v[200:203], v199 offset:6144
	ds_read_b128 v[204:207], v199 offset:7168
	global_load_lds_dwordx4 v152, vcc
	s_add_i32 m0, s2, 0xe000
	s_nop 0
	global_load_lds_dwordx4 v154, vcc
	s_cmp_lg_u32 s65, 1
	s_cselect_b64 s[100:101], s[22:23], 0
	s_and_b64 s[100:101], s[100:101], exec
	s_cbranch_scc0 .Lrestag_up
	s_barrier
.Lrestag_up:
	s_waitcnt lgkmcnt(0)
	s_setprio 1
	s_barrier
	v_mfma_f32_16x16x32_bf16 v[142:145], v[114:117], v[168:171], 0
	v_mfma_f32_16x16x32_bf16 v[62:65], v[130:133], v[168:171], 0
	v_mfma_f32_16x16x32_bf16 v[122:125], v[114:117], v[176:179], 0
	v_mfma_f32_16x16x32_bf16 v[50:53], v[130:133], v[176:179], 0
	v_mfma_f32_16x16x32_bf16 v[106:109], v[114:117], v[184:187], 0
	v_mfma_f32_16x16x32_bf16 v[42:45], v[130:133], v[184:187], 0
	v_mfma_f32_16x16x32_bf16 v[98:101], v[114:117], v[200:203], 0
	v_mfma_f32_16x16x32_bf16 v[34:37], v[130:133], v[200:203], 0
	v_mfma_f32_16x16x32_bf16 v[142:145], v[118:121], v[172:175], v[142:145]
	v_mfma_f32_16x16x32_bf16 v[62:65], v[138:141], v[172:175], v[62:65]
	v_mfma_f32_16x16x32_bf16 v[122:125], v[118:121], v[180:183], v[122:125]
	v_mfma_f32_16x16x32_bf16 v[50:53], v[138:141], v[180:183], v[50:53]
	v_mfma_f32_16x16x32_bf16 v[106:109], v[118:121], v[188:191], v[106:109]
	v_mfma_f32_16x16x32_bf16 v[42:45], v[138:141], v[188:191], v[42:45]
	v_mfma_f32_16x16x32_bf16 v[98:101], v[118:121], v[204:207], v[98:101]
	v_mfma_f32_16x16x32_bf16 v[34:37], v[138:141], v[204:207], v[34:37]
	v_mfma_f32_16x16x32_bf16 v[134:137], v[146:149], v[168:171], 0
	v_mfma_f32_16x16x32_bf16 v[58:61], v[160:163], v[168:171], 0
	v_mfma_f32_16x16x32_bf16 v[126:129], v[146:149], v[176:179], 0
	v_mfma_f32_16x16x32_bf16 v[54:57], v[160:163], v[176:179], 0
	v_mfma_f32_16x16x32_bf16 v[110:113], v[146:149], v[184:187], 0
	v_mfma_f32_16x16x32_bf16 v[46:49], v[160:163], v[184:187], 0
	v_mfma_f32_16x16x32_bf16 v[102:105], v[146:149], v[200:203], 0
	v_mfma_f32_16x16x32_bf16 v[38:41], v[160:163], v[200:203], 0
	v_mfma_f32_16x16x32_bf16 v[134:137], v[156:159], v[172:175], v[134:137]
	v_mfma_f32_16x16x32_bf16 v[58:61], v[164:167], v[172:175], v[58:61]
	v_mfma_f32_16x16x32_bf16 v[126:129], v[156:159], v[180:183], v[126:129]
	v_mfma_f32_16x16x32_bf16 v[54:57], v[164:167], v[180:183], v[54:57]
	v_mfma_f32_16x16x32_bf16 v[110:113], v[156:159], v[188:191], v[110:113]
	v_mfma_f32_16x16x32_bf16 v[46:49], v[164:167], v[188:191], v[46:49]
	v_mfma_f32_16x16x32_bf16 v[102:105], v[156:159], v[204:207], v[102:105]
	v_mfma_f32_16x16x32_bf16 v[38:41], v[164:167], v[204:207], v[38:41]
	s_barrier
	s_setprio 0
	s_add_i32 s84, s84, s1
	s_add_u32 s100, s10, 0x80
	s_addc_u32 s101, s11, 0
	s_mov_b32 m0, s84
	ds_read_b128 v[168:171], v199 offset:16384
	ds_read_b128 v[172:175], v199 offset:17408
	ds_read_b128 v[176:179], v199 offset:18432
	ds_read_b128 v[180:183], v199 offset:19456
	ds_read_b128 v[184:187], v199 offset:20480
	ds_read_b128 v[188:191], v199 offset:21504
	ds_read_b128 v[200:203], v199 offset:22528
	ds_read_b128 v[204:207], v199 offset:23552
	global_load_lds_dwordx4 v0, s[10:11]
	s_add_i32 m0, s84, 0x2000
	s_add_u32 s84, s10, 0x80000
	s_addc_u32 s85, s11, 0
	s_add_i32 s93, s93, s1
	global_load_lds_dwordx4 v150, s[10:11]
	s_mov_b32 m0, s93
	s_add_u32 s98, s68, 0x80
	s_addc_u32 s99, s69, 0
	global_load_lds_dwordx4 v0, s[84:85]
	s_add_i32 m0, s93, 0x2000
	s_nop 0
	global_load_lds_dwordx4 v150, s[84:85]
	s_mov_b32 m0, s2
	s_nop 0
	global_load_lds_dwordx4 v0, s[68:69]
	s_mov_b32 m0, s4
	s_nop 0
	global_load_lds_dwordx4 v150, s[68:69]
	s_waitcnt vmcnt(8) lgkmcnt(0)
	s_setprio 1
	s_barrier
; #define PG8_STAGE(bufoff, gbase, voff) do { _Pragma("unroll") for (int _i = 0; _i < 2; ++_i) \
;         __builtin_amdgcn_global_load_lds((const unsigned*)((const char*)(gbase) + (voff)[_i]), (PG8_LAS unsigned*)(lds + (bufoff) + ldsw + _i * 8192), 16, 0, 0); } while (0)
; #define PG8_LDA(dst, b, h) do { _Pragma("unroll") for (int m = 0; m < 4; ++m) _Pragma("unroll") for (int k = 0; k < 2; ++k) dst[m][k] = *(const PG8_LAS bf16x8*)(lds + PG8_SA(b, h) + aoff + m * 2048 + k * 1024); } while (0)
; #define PG8_LDB(dst, b, h) do { _Pragma("unroll") for (int n = 0; n < 2; ++n) _Pragma("unroll") for (int k = 0; k < 2; ++k) dst[n][k] = *(const PG8_LAS bf16x8*)(lds + PG8_SB(b, h) + boff + n * 2048 + k * 1024); } while (0)
; #define PG8_MMA(ai, bj, At, Bt) do { __builtin_amdgcn_s_setprio(1); _Pragma("unroll") for (int m = 0; m < 4; ++m) _Pragma("unroll") for (int n = 0; n < 2; ++n) _Pragma("unroll") for (int k = 0; k < 2; ++k) \
;         acc[ai][bj][m][n] = __builtin_amdgcn_mfma_f32_16x16x32_bf16(Bt[n][k], At[m][k], acc[ai][bj][m][n], 0, 0, 0); __builtin_amdgcn_s_setprio(0); } while (0)
; #define PG8_WAIT_V(n) asm volatile("s_waitcnt vmcnt(" #n ")" ::: "memory")
; #define PG8_WAIT_L(n) asm volatile("s_waitcnt lgkmcnt(" #n ")" ::: "memory")
; #define PG8_BAR __builtin_amdgcn_s_barrier()
; #define PG8_SCHED __builtin_amdgcn_sched_barrier(0)
; template <class Epi, class Sched, bool ALIGN_EPI = false, bool SP2 = false>
; __device__ __forceinline__ void gemm_phase(PG8_LAS unsigned char* lds, const Gemm g, const Sched& S, const Epi& E) {
;     ...
;             PG8_LDA(At, 0, 1); PG8_STAGE(PG8_SB(0, 0), b2, voffB); PG8_STAGE(PG8_SB(0, 1), b2 + hstep, voffB); PG8_STAGE(PG8_SA(0, 0), a2, voffA);
;             PG8_WAIT_V(8); PG8_WAIT_L(0); PG8_BAR; PG8_MMA(1, 0, At, B0); PG8_MMA(1, 1, At, B1); PG8_BAR; PG8_SCHED;
;             PG8_LDB(B0, 1, 0); PG8_LDB(B1, 1, 1); PG8_SCHED; PG8_LDA(At, 1, 0); PG8_STAGE(PG8_SA(0, 1), a2 + hstep, voffA);
;             PG8_WAIT_V(8); PG8_WAIT_L(0); PG8_BAR; PG8_MMA(0, 0, At, B0); PG8_MMA(0, 1, At, B1); PG8_BAR; PG8_SCHED;
	v_mfma_f32_16x16x32_bf16 v[94:97], v[114:117], v[168:171], 0
	v_mfma_f32_16x16x32_bf16 v[30:33], v[130:133], v[168:171], 0
	v_mfma_f32_16x16x32_bf16 v[82:85], v[114:117], v[176:179], 0
	v_mfma_f32_16x16x32_bf16 v[18:21], v[130:133], v[176:179], 0
	v_mfma_f32_16x16x32_bf16 v[74:77], v[114:117], v[184:187], 0
	v_mfma_f32_16x16x32_bf16 v[10:13], v[130:133], v[184:187], 0
	v_mfma_f32_16x16x32_bf16 v[66:69], v[114:117], v[200:203], 0
	v_mfma_f32_16x16x32_bf16 v[2:5], v[130:133], v[200:203], 0
	v_mfma_f32_16x16x32_bf16 v[94:97], v[118:121], v[172:175], v[94:97]
	v_mfma_f32_16x16x32_bf16 v[30:33], v[138:141], v[172:175], v[30:33]
	v_mfma_f32_16x16x32_bf16 v[82:85], v[118:121], v[180:183], v[82:85]
	v_mfma_f32_16x16x32_bf16 v[18:21], v[138:141], v[180:183], v[18:21]
	v_mfma_f32_16x16x32_bf16 v[74:77], v[118:121], v[188:191], v[74:77]
	v_mfma_f32_16x16x32_bf16 v[10:13], v[138:141], v[188:191], v[10:13]
	v_mfma_f32_16x16x32_bf16 v[66:69], v[118:121], v[204:207], v[66:69]
	v_mfma_f32_16x16x32_bf16 v[2:5], v[138:141], v[204:207], v[2:5]
	v_mfma_f32_16x16x32_bf16 v[90:93], v[146:149], v[168:171], 0
	v_mfma_f32_16x16x32_bf16 v[26:29], v[160:163], v[168:171], 0
	v_mfma_f32_16x16x32_bf16 v[86:89], v[146:149], v[176:179], 0
	v_mfma_f32_16x16x32_bf16 v[22:25], v[160:163], v[176:179], 0
	v_mfma_f32_16x16x32_bf16 v[78:81], v[146:149], v[184:187], 0
	v_mfma_f32_16x16x32_bf16 v[14:17], v[160:163], v[184:187], 0
	v_mfma_f32_16x16x32_bf16 v[70:73], v[146:149], v[200:203], 0
	v_mfma_f32_16x16x32_bf16 v[6:9], v[160:163], v[200:203], 0
	v_mfma_f32_16x16x32_bf16 v[90:93], v[156:159], v[172:175], v[90:93]
	v_mfma_f32_16x16x32_bf16 v[26:29], v[164:167], v[172:175], v[26:29]
	v_mfma_f32_16x16x32_bf16 v[86:89], v[156:159], v[180:183], v[86:89]
	v_mfma_f32_16x16x32_bf16 v[22:25], v[164:167], v[180:183], v[22:25]
	v_mfma_f32_16x16x32_bf16 v[78:81], v[156:159], v[188:191], v[78:81]
	v_mfma_f32_16x16x32_bf16 v[14:17], v[164:167], v[188:191], v[14:17]
	v_mfma_f32_16x16x32_bf16 v[70:73], v[156:159], v[204:207], v[70:73]
	v_mfma_f32_16x16x32_bf16 v[6:9], v[164:167], v[204:207], v[6:9]
	s_barrier
	s_setprio 0
	s_add_i32 s84, 0, 0x18000
	s_add_i32 s85, 0, 0x1c000
	ds_read_b128 v[114:117], v218 offset:32768
	ds_read_b128 v[118:121], v218 offset:33792
	ds_read_b128 v[130:133], v218 offset:34816
	ds_read_b128 v[138:141], v218 offset:35840
	ds_read_b128 v[146:149], v218 offset:49152
	ds_read_b128 v[156:159], v218 offset:50176
	ds_read_b128 v[160:163], v218 offset:51200
	ds_read_b128 v[164:167], v218 offset:52224
	s_add_u32 s68, s68, 0x80000
	s_addc_u32 s69, s69, 0
	s_mov_b32 m0, s5
	ds_read_b128 v[168:171], v199 offset:32768
	ds_read_b128 v[172:175], v199 offset:33792
	ds_read_b128 v[176:179], v199 offset:34816
	ds_read_b128 v[180:183], v199 offset:35840
	ds_read_b128 v[184:187], v199 offset:36864
	ds_read_b128 v[188:191], v199 offset:37888
	ds_read_b128 v[200:203], v199 offset:38912
	ds_read_b128 v[204:207], v199 offset:39936
	global_load_lds_dwordx4 v0, s[68:69]
	s_mov_b32 m0, s6
	s_nop 0
	global_load_lds_dwordx4 v150, s[68:69]
	s_waitcnt vmcnt(8) lgkmcnt(0)
	s_setprio 1
	s_barrier
	v_mfma_f32_16x16x32_bf16 v[142:145], v[114:117], v[168:171], v[142:145]
	v_mfma_f32_16x16x32_bf16 v[62:65], v[130:133], v[168:171], v[62:65]
	v_mfma_f32_16x16x32_bf16 v[122:125], v[114:117], v[176:179], v[122:125]
	v_mfma_f32_16x16x32_bf16 v[50:53], v[130:133], v[176:179], v[50:53]
	v_mfma_f32_16x16x32_bf16 v[106:109], v[114:117], v[184:187], v[106:109]
	v_mfma_f32_16x16x32_bf16 v[42:45], v[130:133], v[184:187], v[42:45]
	v_mfma_f32_16x16x32_bf16 v[98:101], v[114:117], v[200:203], v[98:101]
	v_mfma_f32_16x16x32_bf16 v[34:37], v[130:133], v[200:203], v[34:37]
	v_mfma_f32_16x16x32_bf16 v[142:145], v[118:121], v[172:175], v[142:145]
	v_mfma_f32_16x16x32_bf16 v[62:65], v[138:141], v[172:175], v[62:65]
	v_mfma_f32_16x16x32_bf16 v[122:125], v[118:121], v[180:183], v[122:125]
	v_mfma_f32_16x16x32_bf16 v[50:53], v[138:141], v[180:183], v[50:53]
	v_mfma_f32_16x16x32_bf16 v[106:109], v[118:121], v[188:191], v[106:109]
	v_mfma_f32_16x16x32_bf16 v[42:45], v[138:141], v[188:191], v[42:45]
	v_mfma_f32_16x16x32_bf16 v[98:101], v[118:121], v[204:207], v[98:101]
	v_mfma_f32_16x16x32_bf16 v[34:37], v[138:141], v[204:207], v[34:37]
	v_mfma_f32_16x16x32_bf16 v[134:137], v[146:149], v[168:171], v[134:137]
	v_mfma_f32_16x16x32_bf16 v[58:61], v[160:163], v[168:171], v[58:61]
	v_mfma_f32_16x16x32_bf16 v[126:129], v[146:149], v[176:179], v[126:129]
	v_mfma_f32_16x16x32_bf16 v[54:57], v[160:163], v[176:179], v[54:57]
	v_mfma_f32_16x16x32_bf16 v[110:113], v[146:149], v[184:187], v[110:113]
	v_mfma_f32_16x16x32_bf16 v[46:49], v[160:163], v[184:187], v[46:49]
	v_mfma_f32_16x16x32_bf16 v[102:105], v[146:149], v[200:203], v[102:105]
	v_mfma_f32_16x16x32_bf16 v[38:41], v[160:163], v[200:203], v[38:41]
	v_mfma_f32_16x16x32_bf16 v[134:137], v[156:159], v[172:175], v[134:137]
	v_mfma_f32_16x16x32_bf16 v[58:61], v[164:167], v[172:175], v[58:61]
	v_mfma_f32_16x16x32_bf16 v[126:129], v[156:159], v[180:183], v[126:129]
	v_mfma_f32_16x16x32_bf16 v[54:57], v[164:167], v[180:183], v[54:57]
	v_mfma_f32_16x16x32_bf16 v[110:113], v[156:159], v[188:191], v[110:113]
	v_mfma_f32_16x16x32_bf16 v[46:49], v[164:167], v[188:191], v[46:49]
	v_mfma_f32_16x16x32_bf16 v[102:105], v[156:159], v[204:207], v[102:105]
	v_mfma_f32_16x16x32_bf16 v[38:41], v[164:167], v[204:207], v[38:41]
	s_barrier
; #define PG8_STAGE(bufoff, gbase, voff) do { _Pragma("unroll") for (int _i = 0; _i < 2; ++_i) \
;         __builtin_amdgcn_global_load_lds((const unsigned*)((const char*)(gbase) + (voff)[_i]), (PG8_LAS unsigned*)(lds + (bufoff) + ldsw + _i * 8192), 16, 0, 0); } while (0)
; #define PG8_LDA(dst, b, h) do { _Pragma("unroll") for (int m = 0; m < 4; ++m) _Pragma("unroll") for (int k = 0; k < 2; ++k) dst[m][k] = *(const PG8_LAS bf16x8*)(lds + PG8_SA(b, h) + aoff + m * 2048 + k * 1024); } while (0)
; #define PG8_MMA(ai, bj, At, Bt) do { __builtin_amdgcn_s_setprio(1); _Pragma("unroll") for (int m = 0; m < 4; ++m) _Pragma("unroll") for (int n = 0; n < 2; ++n) _Pragma("unroll") for (int k = 0; k < 2; ++k) \
;         acc[ai][bj][m][n] = __builtin_amdgcn_mfma_f32_16x16x32_bf16(Bt[n][k], At[m][k], acc[ai][bj][m][n], 0, 0, 0); __builtin_amdgcn_s_setprio(0); } while (0)
; #define PG8_WAIT_V(n) asm volatile("s_waitcnt vmcnt(" #n ")" ::: "memory")
; #define PG8_WAIT_L(n) asm volatile("s_waitcnt lgkmcnt(" #n ")" ::: "memory")
; #define PG8_BAR __builtin_amdgcn_s_barrier()
; #define PG8_SCHED __builtin_amdgcn_sched_barrier(0)
; template <class Epi, class Sched, bool ALIGN_EPI = false, bool SP2 = false>
; __device__ __forceinline__ void gemm_phase(PG8_LAS unsigned char* lds, const Gemm g, const Sched& S, const Epi& E) {
;     ...
;             PG8_LDA(At, 1, 1); PG8_STAGE(PG8_SB(1, 0), b3, voffB); PG8_STAGE(PG8_SB(1, 1), b3 + hstep, voffB); PG8_STAGE(PG8_SA(1, 0), a3, voffA);
;             PG8_WAIT_V(8); PG8_WAIT_L(0); PG8_BAR; PG8_MMA(1, 0, At, B0); PG8_MMA(1, 1, At, B1); PG8_BAR; PG8_SCHED;
	s_setprio 0
	s_add_i32 s68, s84, s1
	s_mov_b32 m0, s68
	ds_read_b128 v[168:171], v199 offset:49152
	ds_read_b128 v[172:175], v199 offset:50176
	ds_read_b128 v[176:179], v199 offset:51200
	ds_read_b128 v[180:183], v199 offset:52224
	ds_read_b128 v[184:187], v199 offset:53248
	ds_read_b128 v[188:191], v199 offset:54272
	ds_read_b128 v[200:203], v199 offset:55296
	ds_read_b128 v[204:207], v199 offset:56320
	global_load_lds_dwordx4 v0, s[100:101]
	s_add_i32 m0, s68, 0x2000
	s_add_i32 s68, s85, s1
	global_load_lds_dwordx4 v150, s[100:101]
	s_add_u32 s10, s10, 0x80080
	s_addc_u32 s11, s11, 0
	s_mov_b32 m0, s68
	s_nop 0
	global_load_lds_dwordx4 v0, s[10:11]
	s_add_i32 m0, s68, 0x2000
	s_nop 0
	global_load_lds_dwordx4 v150, s[10:11]
	s_mov_b32 m0, s7
	s_nop 0
	global_load_lds_dwordx4 v0, s[98:99]
	s_mov_b32 m0, s30
	s_nop 0
	global_load_lds_dwordx4 v150, s[98:99]
	s_waitcnt vmcnt(8) lgkmcnt(0)
	s_setprio 1
	s_barrier
	v_mfma_f32_16x16x32_bf16 v[94:97], v[114:117], v[168:171], v[94:97]
	v_mfma_f32_16x16x32_bf16 v[30:33], v[130:133], v[168:171], v[30:33]
	v_mfma_f32_16x16x32_bf16 v[82:85], v[114:117], v[176:179], v[82:85]
	v_mfma_f32_16x16x32_bf16 v[18:21], v[130:133], v[176:179], v[18:21]
	v_mfma_f32_16x16x32_bf16 v[74:77], v[114:117], v[184:187], v[74:77]
	v_mfma_f32_16x16x32_bf16 v[10:13], v[130:133], v[184:187], v[10:13]
	v_mfma_f32_16x16x32_bf16 v[66:69], v[114:117], v[200:203], v[66:69]
	v_mfma_f32_16x16x32_bf16 v[2:5], v[130:133], v[200:203], v[2:5]
	v_mfma_f32_16x16x32_bf16 v[94:97], v[118:121], v[172:175], v[94:97]
	v_mfma_f32_16x16x32_bf16 v[30:33], v[138:141], v[172:175], v[30:33]
	v_mfma_f32_16x16x32_bf16 v[82:85], v[118:121], v[180:183], v[82:85]
	v_mfma_f32_16x16x32_bf16 v[18:21], v[138:141], v[180:183], v[18:21]
	v_mfma_f32_16x16x32_bf16 v[74:77], v[118:121], v[188:191], v[74:77]
	v_mfma_f32_16x16x32_bf16 v[10:13], v[138:141], v[188:191], v[10:13]
	v_mfma_f32_16x16x32_bf16 v[66:69], v[118:121], v[204:207], v[66:69]
	v_mfma_f32_16x16x32_bf16 v[2:5], v[138:141], v[204:207], v[2:5]
	v_mfma_f32_16x16x32_bf16 v[90:93], v[146:149], v[168:171], v[90:93]
	v_mfma_f32_16x16x32_bf16 v[26:29], v[160:163], v[168:171], v[26:29]
	v_mfma_f32_16x16x32_bf16 v[86:89], v[146:149], v[176:179], v[86:89]
	v_mfma_f32_16x16x32_bf16 v[22:25], v[160:163], v[176:179], v[22:25]
	v_mfma_f32_16x16x32_bf16 v[78:81], v[146:149], v[184:187], v[78:81]
	v_mfma_f32_16x16x32_bf16 v[14:17], v[160:163], v[184:187], v[14:17]
	v_mfma_f32_16x16x32_bf16 v[70:73], v[146:149], v[200:203], v[70:73]
	v_mfma_f32_16x16x32_bf16 v[6:9], v[160:163], v[200:203], v[6:9]
	v_mfma_f32_16x16x32_bf16 v[90:93], v[156:159], v[172:175], v[90:93]
	v_mfma_f32_16x16x32_bf16 v[26:29], v[164:167], v[172:175], v[26:29]
	v_mfma_f32_16x16x32_bf16 v[86:89], v[156:159], v[180:183], v[86:89]
	v_mfma_f32_16x16x32_bf16 v[22:25], v[164:167], v[180:183], v[22:25]
	v_mfma_f32_16x16x32_bf16 v[78:81], v[156:159], v[188:191], v[78:81]
	v_mfma_f32_16x16x32_bf16 v[14:17], v[164:167], v[188:191], v[14:17]
	v_mfma_f32_16x16x32_bf16 v[70:73], v[156:159], v[204:207], v[70:73]
	v_mfma_f32_16x16x32_bf16 v[6:9], v[164:167], v[204:207], v[6:9]
	s_barrier
	s_setprio 0
	s_add_i32 s13, s13, 2
	s_add_u32 vcc_lo, vcc_lo, 0x100
	s_addc_u32 vcc_hi, vcc_hi, 0
	s_add_u32 s21, s21, 0x100
	s_addc_u32 s12, s12, 0

; #define PG8_BAR __builtin_amdgcn_s_barrier()
; template <class Epi, class Sched, bool ALIGN_EPI = false, bool SP2 = false>
; __device__ __forceinline__ void gemm_phase(PG8_LAS unsigned char* lds, const Gemm g, const Sched& S, const Epi& E) {
;     ...
;         if constexpr (!Epi::AFTER_DRAIN) { E(acc, cur, wr, wc, fr, fq); S.done(cur); }
;         if (!has_next) break;
; #pragma unroll
;         for (int a = 0; a < 2; ++a)
; #pragma unroll
;             for (int b = 0; b < 2; ++b)
; #pragma unroll
;                 for (int m = 0; m < 4; ++m)
; #pragma unroll
;                     for (int n = 0; n < 2; ++n) acc[a][b][m][n] = (f32x4){0.f, 0.f, 0.f, 0.f};
;         cur = nxt; cA = nA; cB = nB; ++ui;
;         if constexpr (ALIGN_EPI) { if (wr == 1) PG8_BAR; }
.LBB0_65:
	s_or_b64 exec, exec, s[10:11]
	s_andn2_b64 vcc, exec, s[46:47]
	s_mov_b64 s[10:11], -1
	s_cbranch_vccnz .LBB0_34
	s_andn2_b64 vcc, exec, s[22:23]
	s_cbranch_vccnz .LBB0_33
	s_branch .LBB0_33

; #define PG8_STAGE(bufoff, gbase, voff) do { _Pragma("unroll") for (int _i = 0; _i < 2; ++_i) \
;         __builtin_amdgcn_global_load_lds((const unsigned*)((const char*)(gbase) + (voff)[_i]), (PG8_LAS unsigned*)(lds + (bufoff) + ldsw + _i * 8192), 16, 0, 0); } while (0)
; #define PG8_LDA(dst, b, h) do { _Pragma("unroll") for (int m = 0; m < 4; ++m) _Pragma("unroll") for (int k = 0; k < 2; ++k) dst[m][k] = *(const PG8_LAS bf16x8*)(lds + PG8_SA(b, h) + aoff + m * 2048 + k * 1024); } while (0)
; #define PG8_LDB(dst, b, h) do { _Pragma("unroll") for (int n = 0; n < 2; ++n) _Pragma("unroll") for (int k = 0; k < 2; ++k) dst[n][k] = *(const PG8_LAS bf16x8*)(lds + PG8_SB(b, h) + boff + n * 2048 + k * 1024); } while (0)
; #define PG8_MMA(ai, bj, At, Bt) do { __builtin_amdgcn_s_setprio(1); _Pragma("unroll") for (int m = 0; m < 4; ++m) _Pragma("unroll") for (int n = 0; n < 2; ++n) _Pragma("unroll") for (int k = 0; k < 2; ++k) \
;         acc[ai][bj][m][n] = __builtin_amdgcn_mfma_f32_16x16x32_bf16(Bt[n][k], At[m][k], acc[ai][bj][m][n], 0, 0, 0); __builtin_amdgcn_s_setprio(0); } while (0)
; #define PG8_WAIT_V(n) asm volatile("s_waitcnt vmcnt(" #n ")" ::: "memory")
; #define PG8_WAIT_L(n) asm volatile("s_waitcnt lgkmcnt(" #n ")" ::: "memory")
; template <class Epi, class Sched, bool ALIGN_EPI = false, bool SP2 = false>
; __device__ __forceinline__ void gemm_phase(PG8_LAS unsigned char* lds, const Gemm g, const Sched& S, const Epi& E) {
;     ...
;         const char* nA = has_next ? (const char*)g.A + (size_t)nxt.pm * tstep : cA; const char* nB = has_next ? (const char*)g.Bt + (size_t)nxt.pn * tstep : cB;
;         for (int t = 0; t < nt; t += 2) {
;             const bool last = (t == nt - 2);
;             const char* a1 = cA + (size_t)(t + 1) * kstep;
;             const char* a2 = last ? nA : cA + (size_t)(t + 2) * kstep; const char* b2 = last ? nB : cB + (size_t)(t + 2) * kstep;
;             const char* a3 = a2 + kstep; const char* b3 = b2 + kstep;
;             if (last && has_next) S.a_ready(nxt);
;             if constexpr (SP2) {
;             PG8_LDB(B0, 0, 0); PG8_LDB(B1, 0, 1); PG8_SCHED; PG8_LDA(At, 0, 0); PG8_STAGE(PG8_SA(1, 1), a1 + hstep, voffA);
;             PG8_WAIT_V(8); PG8_WAIT_L(0); PG8_BAR; PG8_MMA(0, 0, At, B0); PG8_MMA(0, 1, At, B1); PG8_BAR; PG8_SCHED;
;     ...
;         if constexpr (ALIGN_EPI) { if (wr == 1) PG8_BAR; }
.Lstg4_done:
	s_ashr_i32 s37, s36, 31
	s_lshl_b64 s[26:27], s[36:37], 20
	s_add_u32 s26, s18, s26
	s_addc_u32 s27, s19, s27
	s_and_b64 s[44:45], s[40:41], exec
	s_cselect_b32 s37, s27, s51
	s_cselect_b32 s43, s26, s50
	s_ashr_i32 s23, s22, 31
	s_lshl_b64 s[44:45], s[22:23], 20
	s_add_u32 s44, s96, s44
	s_addc_u32 s45, s97, s45
	s_and_b64 s[52:53], s[40:41], exec
	s_cselect_b32 s23, s45, s11
	s_cselect_b32 s56, s44, s10
	s_add_u32 s50, s50, 0x80080
	s_addc_u32 s51, s51, 0
	s_add_u32 s57, s10, 0x100
	s_addc_u32 s58, s11, 0
	s_mov_b32 s59, -2
	v_add_u32_e32 v248, 0x10000, v149
	s_add_u32 s10, s50, 0xfff80080
	s_addc_u32 s11, s51, -1
	s_add_i32 s60, 0, 0x10000
	s_cmp_eq_u32 s59, 28
	s_cselect_b32 s53, s37, s11
	s_cselect_b32 s52, s43, s10
	s_cselect_b32 s11, s23, s58
	s_cselect_b32 s10, s56, s57
	s_add_i32 s62, 0, 0x14000
	ds_read_b128 v[140:143], v248
	ds_read_b128 v[152:155], v248 offset:1024
	ds_read_b128 v[156:159], v248 offset:2048
	ds_read_b128 v[160:163], v248 offset:3072
	ds_read_b128 v[164:167], v248 offset:16384
	ds_read_b128 v[168:171], v248 offset:17408
	ds_read_b128 v[172:175], v248 offset:18432
	ds_read_b128 v[176:179], v248 offset:19456
	s_add_i32 m0, s5, 0xc000
	ds_read_b128 v[180:183], v151
	ds_read_b128 v[184:187], v151 offset:1024
	ds_read_b128 v[188:191], v151 offset:2048
	ds_read_b128 v[192:195], v151 offset:3072
	ds_read_b128 v[196:199], v151 offset:4096
	ds_read_b128 v[200:203], v151 offset:5120
	ds_read_b128 v[204:207], v151 offset:6144
	ds_read_b128 v[208:211], v151 offset:7168
	global_load_lds_dwordx4 v136, s[50:51]
	s_add_i32 m0, s5, 0xe000
	s_nop 0
	global_load_lds_dwordx4 v138, s[50:51]
	s_cmp_lg_u32 s55, 1
	s_cselect_b64 s[100:101], s[8:9], 0
	s_and_b64 s[100:101], s[100:101], exec
	s_cbranch_scc0 .Lrestag_proj
	s_barrier
.Lrestag_proj:
	s_waitcnt lgkmcnt(0)
	s_setprio 1
	s_barrier
	v_mfma_f32_16x16x32_bf16 v[126:129], v[140:143], v[180:183], 0
	v_mfma_f32_16x16x32_bf16 v[122:125], v[156:159], v[180:183], 0
	v_mfma_f32_16x16x32_bf16 v[110:113], v[140:143], v[188:191], 0
	v_mfma_f32_16x16x32_bf16 v[106:109], v[156:159], v[188:191], 0
	v_mfma_f32_16x16x32_bf16 v[94:97], v[140:143], v[196:199], 0
	v_mfma_f32_16x16x32_bf16 v[90:93], v[156:159], v[196:199], 0
	v_mfma_f32_16x16x32_bf16 v[78:81], v[140:143], v[204:207], 0
	v_mfma_f32_16x16x32_bf16 v[74:77], v[156:159], v[204:207], 0
	v_mfma_f32_16x16x32_bf16 v[126:129], v[152:155], v[184:187], v[126:129]
	v_mfma_f32_16x16x32_bf16 v[122:125], v[160:163], v[184:187], v[122:125]
	v_mfma_f32_16x16x32_bf16 v[110:113], v[152:155], v[192:195], v[110:113]
	v_mfma_f32_16x16x32_bf16 v[106:109], v[160:163], v[192:195], v[106:109]
	v_mfma_f32_16x16x32_bf16 v[94:97], v[152:155], v[200:203], v[94:97]
	v_mfma_f32_16x16x32_bf16 v[90:93], v[160:163], v[200:203], v[90:93]
	v_mfma_f32_16x16x32_bf16 v[78:81], v[152:155], v[208:211], v[78:81]
	v_mfma_f32_16x16x32_bf16 v[74:77], v[160:163], v[208:211], v[74:77]
	v_mfma_f32_16x16x32_bf16 v[118:121], v[164:167], v[180:183], 0
	v_mfma_f32_16x16x32_bf16 v[114:117], v[172:175], v[180:183], 0
	v_mfma_f32_16x16x32_bf16 v[102:105], v[164:167], v[188:191], 0
	v_mfma_f32_16x16x32_bf16 v[98:101], v[172:175], v[188:191], 0
	v_mfma_f32_16x16x32_bf16 v[86:89], v[164:167], v[196:199], 0
	v_mfma_f32_16x16x32_bf16 v[82:85], v[172:175], v[196:199], 0
	v_mfma_f32_16x16x32_bf16 v[70:73], v[164:167], v[204:207], 0
	v_mfma_f32_16x16x32_bf16 v[66:69], v[172:175], v[204:207], 0
	v_mfma_f32_16x16x32_bf16 v[118:121], v[168:171], v[184:187], v[118:121]
	v_mfma_f32_16x16x32_bf16 v[114:117], v[176:179], v[184:187], v[114:117]
	v_mfma_f32_16x16x32_bf16 v[102:105], v[168:171], v[192:195], v[102:105]
	v_mfma_f32_16x16x32_bf16 v[98:101], v[176:179], v[192:195], v[98:101]
	v_mfma_f32_16x16x32_bf16 v[86:89], v[168:171], v[200:203], v[86:89]
	v_mfma_f32_16x16x32_bf16 v[82:85], v[176:179], v[200:203], v[82:85]
	v_mfma_f32_16x16x32_bf16 v[70:73], v[168:171], v[208:211], v[70:73]
	v_mfma_f32_16x16x32_bf16 v[66:69], v[176:179], v[208:211], v[66:69]
	s_barrier
	s_setprio 0
	s_add_i32 s60, s60, s4
	s_add_u32 s100, s10, 0x80
	s_addc_u32 s101, s11, 0
	s_mov_b32 m0, s60
	ds_read_b128 v[180:183], v151 offset:16384
	ds_read_b128 v[184:187], v151 offset:17408
	ds_read_b128 v[188:191], v151 offset:18432
	ds_read_b128 v[192:195], v151 offset:19456
	ds_read_b128 v[196:199], v151 offset:20480
	ds_read_b128 v[200:203], v151 offset:21504
	ds_read_b128 v[204:207], v151 offset:22528
	ds_read_b128 v[208:211], v151 offset:23552
	global_load_lds_dwordx4 v0, s[10:11]
	s_add_i32 m0, s60, 0x2000
	s_add_u32 s60, s10, 0x80000
	s_addc_u32 s61, s11, 0
	s_add_i32 s62, s62, s4
	global_load_lds_dwordx4 v134, s[10:11]
	s_mov_b32 m0, s62
	s_add_u32 s98, s52, 0x80
	s_addc_u32 s99, s53, 0
	global_load_lds_dwordx4 v0, s[60:61]
	s_add_i32 m0, s62, 0x2000
	s_nop 0
	global_load_lds_dwordx4 v134, s[60:61]
	s_mov_b32 m0, s5
	s_nop 0
	global_load_lds_dwordx4 v130, s[52:53]
	s_mov_b32 m0, s6
	s_nop 0
	global_load_lds_dwordx4 v132, s[52:53]
	s_waitcnt vmcnt(8) lgkmcnt(0)
	s_setprio 1
	s_barrier
; #define PG8_STAGE(bufoff, gbase, voff) do { _Pragma("unroll") for (int _i = 0; _i < 2; ++_i) \
;         __builtin_amdgcn_global_load_lds((const unsigned*)((const char*)(gbase) + (voff)[_i]), (PG8_LAS unsigned*)(lds + (bufoff) + ldsw + _i * 8192), 16, 0, 0); } while (0)
; #define PG8_LDA(dst, b, h) do { _Pragma("unroll") for (int m = 0; m < 4; ++m) _Pragma("unroll") for (int k = 0; k < 2; ++k) dst[m][k] = *(const PG8_LAS bf16x8*)(lds + PG8_SA(b, h) + aoff + m * 2048 + k * 1024); } while (0)
; #define PG8_LDB(dst, b, h) do { _Pragma("unroll") for (int n = 0; n < 2; ++n) _Pragma("unroll") for (int k = 0; k < 2; ++k) dst[n][k] = *(const PG8_LAS bf16x8*)(lds + PG8_SB(b, h) + boff + n * 2048 + k * 1024); } while (0)
; #define PG8_MMA(ai, bj, At, Bt) do { __builtin_amdgcn_s_setprio(1); _Pragma("unroll") for (int m = 0; m < 4; ++m) _Pragma("unroll") for (int n = 0; n < 2; ++n) _Pragma("unroll") for (int k = 0; k < 2; ++k) \
;         acc[ai][bj][m][n] = __builtin_amdgcn_mfma_f32_16x16x32_bf16(Bt[n][k], At[m][k], acc[ai][bj][m][n], 0, 0, 0); __builtin_amdgcn_s_setprio(0); } while (0)
; #define PG8_WAIT_V(n) asm volatile("s_waitcnt vmcnt(" #n ")" ::: "memory")
; #define PG8_WAIT_L(n) asm volatile("s_waitcnt lgkmcnt(" #n ")" ::: "memory")
; #define PG8_BAR __builtin_amdgcn_s_barrier()
; #define PG8_SCHED __builtin_amdgcn_sched_barrier(0)
; template <class Epi, class Sched, bool ALIGN_EPI = false, bool SP2 = false>
; __device__ __forceinline__ void gemm_phase(PG8_LAS unsigned char* lds, const Gemm g, const Sched& S, const Epi& E) {
;     ...
;             PG8_LDA(At, 0, 1); PG8_STAGE(PG8_SB(0, 0), b2, voffB); PG8_STAGE(PG8_SB(0, 1), b2 + hstep, voffB); PG8_STAGE(PG8_SA(0, 0), a2, voffA);
;             PG8_WAIT_V(8); PG8_WAIT_L(0); PG8_BAR; PG8_MMA(1, 0, At, B0); PG8_MMA(1, 1, At, B1); PG8_BAR; PG8_SCHED;
;             PG8_LDB(B0, 1, 0); PG8_LDB(B1, 1, 1); PG8_SCHED; PG8_LDA(At, 1, 0); PG8_STAGE(PG8_SA(0, 1), a2 + hstep, voffA);
;             PG8_WAIT_V(8); PG8_WAIT_L(0); PG8_BAR; PG8_MMA(0, 0, At, B0); PG8_MMA(0, 1, At, B1); PG8_BAR; PG8_SCHED;
	v_mfma_f32_16x16x32_bf16 v[62:65], v[140:143], v[180:183], 0
	v_mfma_f32_16x16x32_bf16 v[58:61], v[156:159], v[180:183], 0
	v_mfma_f32_16x16x32_bf16 v[46:49], v[140:143], v[188:191], 0
	v_mfma_f32_16x16x32_bf16 v[42:45], v[156:159], v[188:191], 0
	v_mfma_f32_16x16x32_bf16 v[30:33], v[140:143], v[196:199], 0
	v_mfma_f32_16x16x32_bf16 v[26:29], v[156:159], v[196:199], 0
	v_mfma_f32_16x16x32_bf16 v[14:17], v[140:143], v[204:207], 0
	v_mfma_f32_16x16x32_bf16 v[10:13], v[156:159], v[204:207], 0
	v_mfma_f32_16x16x32_bf16 v[62:65], v[152:155], v[184:187], v[62:65]
	v_mfma_f32_16x16x32_bf16 v[58:61], v[160:163], v[184:187], v[58:61]
	v_mfma_f32_16x16x32_bf16 v[46:49], v[152:155], v[192:195], v[46:49]
	v_mfma_f32_16x16x32_bf16 v[42:45], v[160:163], v[192:195], v[42:45]
	v_mfma_f32_16x16x32_bf16 v[30:33], v[152:155], v[200:203], v[30:33]
	v_mfma_f32_16x16x32_bf16 v[26:29], v[160:163], v[200:203], v[26:29]
	v_mfma_f32_16x16x32_bf16 v[14:17], v[152:155], v[208:211], v[14:17]
	v_mfma_f32_16x16x32_bf16 v[10:13], v[160:163], v[208:211], v[10:13]
	v_mfma_f32_16x16x32_bf16 v[54:57], v[164:167], v[180:183], 0
	v_mfma_f32_16x16x32_bf16 v[50:53], v[172:175], v[180:183], 0
	v_mfma_f32_16x16x32_bf16 v[38:41], v[164:167], v[188:191], 0
	v_mfma_f32_16x16x32_bf16 v[34:37], v[172:175], v[188:191], 0
	v_mfma_f32_16x16x32_bf16 v[22:25], v[164:167], v[196:199], 0
	v_mfma_f32_16x16x32_bf16 v[18:21], v[172:175], v[196:199], 0
	v_mfma_f32_16x16x32_bf16 v[6:9], v[164:167], v[204:207], 0
	v_mfma_f32_16x16x32_bf16 v[2:5], v[172:175], v[204:207], 0
	v_mfma_f32_16x16x32_bf16 v[54:57], v[168:171], v[184:187], v[54:57]
	v_mfma_f32_16x16x32_bf16 v[50:53], v[176:179], v[184:187], v[50:53]
	v_mfma_f32_16x16x32_bf16 v[38:41], v[168:171], v[192:195], v[38:41]
	v_mfma_f32_16x16x32_bf16 v[34:37], v[176:179], v[192:195], v[34:37]
	v_mfma_f32_16x16x32_bf16 v[22:25], v[168:171], v[200:203], v[22:25]
	v_mfma_f32_16x16x32_bf16 v[18:21], v[176:179], v[200:203], v[18:21]
	v_mfma_f32_16x16x32_bf16 v[6:9], v[168:171], v[208:211], v[6:9]
	v_mfma_f32_16x16x32_bf16 v[2:5], v[176:179], v[208:211], v[2:5]
	s_barrier
	s_setprio 0
	s_add_i32 s60, 0, 0x18000
	s_add_i32 s61, 0, 0x1c000
	ds_read_b128 v[140:143], v248 offset:32768
	ds_read_b128 v[152:155], v248 offset:33792
	ds_read_b128 v[156:159], v248 offset:34816
	ds_read_b128 v[160:163], v248 offset:35840
	ds_read_b128 v[164:167], v248 offset:49152
	ds_read_b128 v[168:171], v248 offset:50176
	ds_read_b128 v[172:175], v248 offset:51200
	ds_read_b128 v[176:179], v248 offset:52224
	s_add_u32 s52, s52, 0x80000
	s_addc_u32 s53, s53, 0
	s_mov_b32 m0, s7
	ds_read_b128 v[180:183], v151 offset:32768
	ds_read_b128 v[184:187], v151 offset:33792
	ds_read_b128 v[188:191], v151 offset:34816
	ds_read_b128 v[192:195], v151 offset:35840
	ds_read_b128 v[196:199], v151 offset:36864
	ds_read_b128 v[200:203], v151 offset:37888
	ds_read_b128 v[204:207], v151 offset:38912
	ds_read_b128 v[208:211], v151 offset:39936
	global_load_lds_dwordx4 v130, s[52:53]
	s_mov_b32 m0, s17
	s_nop 0
	global_load_lds_dwordx4 v132, s[52:53]
	s_waitcnt vmcnt(8) lgkmcnt(0)
	s_setprio 1
	s_barrier
	v_mfma_f32_16x16x32_bf16 v[126:129], v[140:143], v[180:183], v[126:129]
	v_mfma_f32_16x16x32_bf16 v[122:125], v[156:159], v[180:183], v[122:125]
	v_mfma_f32_16x16x32_bf16 v[110:113], v[140:143], v[188:191], v[110:113]
	v_mfma_f32_16x16x32_bf16 v[106:109], v[156:159], v[188:191], v[106:109]
	v_mfma_f32_16x16x32_bf16 v[94:97], v[140:143], v[196:199], v[94:97]
	v_mfma_f32_16x16x32_bf16 v[90:93], v[156:159], v[196:199], v[90:93]
	v_mfma_f32_16x16x32_bf16 v[78:81], v[140:143], v[204:207], v[78:81]
	v_mfma_f32_16x16x32_bf16 v[74:77], v[156:159], v[204:207], v[74:77]
	v_mfma_f32_16x16x32_bf16 v[126:129], v[152:155], v[184:187], v[126:129]
	v_mfma_f32_16x16x32_bf16 v[122:125], v[160:163], v[184:187], v[122:125]
	v_mfma_f32_16x16x32_bf16 v[110:113], v[152:155], v[192:195], v[110:113]
	v_mfma_f32_16x16x32_bf16 v[106:109], v[160:163], v[192:195], v[106:109]
	v_mfma_f32_16x16x32_bf16 v[94:97], v[152:155], v[200:203], v[94:97]
	v_mfma_f32_16x16x32_bf16 v[90:93], v[160:163], v[200:203], v[90:93]
	v_mfma_f32_16x16x32_bf16 v[78:81], v[152:155], v[208:211], v[78:81]
	v_mfma_f32_16x16x32_bf16 v[74:77], v[160:163], v[208:211], v[74:77]
	v_mfma_f32_16x16x32_bf16 v[118:121], v[164:167], v[180:183], v[118:121]
	v_mfma_f32_16x16x32_bf16 v[114:117], v[172:175], v[180:183], v[114:117]
	v_mfma_f32_16x16x32_bf16 v[102:105], v[164:167], v[188:191], v[102:105]
	v_mfma_f32_16x16x32_bf16 v[98:101], v[172:175], v[188:191], v[98:101]
	v_mfma_f32_16x16x32_bf16 v[86:89], v[164:167], v[196:199], v[86:89]
	v_mfma_f32_16x16x32_bf16 v[82:85], v[172:175], v[196:199], v[82:85]
	v_mfma_f32_16x16x32_bf16 v[70:73], v[164:167], v[204:207], v[70:73]
	v_mfma_f32_16x16x32_bf16 v[66:69], v[172:175], v[204:207], v[66:69]
	v_mfma_f32_16x16x32_bf16 v[118:121], v[168:171], v[184:187], v[118:121]
	v_mfma_f32_16x16x32_bf16 v[114:117], v[176:179], v[184:187], v[114:117]
	v_mfma_f32_16x16x32_bf16 v[102:105], v[168:171], v[192:195], v[102:105]
	v_mfma_f32_16x16x32_bf16 v[98:101], v[176:179], v[192:195], v[98:101]
	v_mfma_f32_16x16x32_bf16 v[86:89], v[168:171], v[200:203], v[86:89]
	v_mfma_f32_16x16x32_bf16 v[82:85], v[176:179], v[200:203], v[82:85]
	v_mfma_f32_16x16x32_bf16 v[70:73], v[168:171], v[208:211], v[70:73]
	v_mfma_f32_16x16x32_bf16 v[66:69], v[176:179], v[208:211], v[66:69]
	s_barrier
; #define PG8_STAGE(bufoff, gbase, voff) do { _Pragma("unroll") for (int _i = 0; _i < 2; ++_i) \
;         __builtin_amdgcn_global_load_lds((const unsigned*)((const char*)(gbase) + (voff)[_i]), (PG8_LAS unsigned*)(lds + (bufoff) + ldsw + _i * 8192), 16, 0, 0); } while (0)
; #define PG8_LDA(dst, b, h) do { _Pragma("unroll") for (int m = 0; m < 4; ++m) _Pragma("unroll") for (int k = 0; k < 2; ++k) dst[m][k] = *(const PG8_LAS bf16x8*)(lds + PG8_SA(b, h) + aoff + m * 2048 + k * 1024); } while (0)
; #define PG8_MMA(ai, bj, At, Bt) do { __builtin_amdgcn_s_setprio(1); _Pragma("unroll") for (int m = 0; m < 4; ++m) _Pragma("unroll") for (int n = 0; n < 2; ++n) _Pragma("unroll") for (int k = 0; k < 2; ++k) \
;         acc[ai][bj][m][n] = __builtin_amdgcn_mfma_f32_16x16x32_bf16(Bt[n][k], At[m][k], acc[ai][bj][m][n], 0, 0, 0); __builtin_amdgcn_s_setprio(0); } while (0)
; #define PG8_WAIT_V(n) asm volatile("s_waitcnt vmcnt(" #n ")" ::: "memory")
; #define PG8_WAIT_L(n) asm volatile("s_waitcnt lgkmcnt(" #n ")" ::: "memory")
; #define PG8_BAR __builtin_amdgcn_s_barrier()
; #define PG8_SCHED __builtin_amdgcn_sched_barrier(0)
; template <class Epi, class Sched, bool ALIGN_EPI = false, bool SP2 = false>
; __device__ __forceinline__ void gemm_phase(PG8_LAS unsigned char* lds, const Gemm g, const Sched& S, const Epi& E) {
;     ...
;             PG8_LDA(At, 1, 1); PG8_STAGE(PG8_SB(1, 0), b3, voffB); PG8_STAGE(PG8_SB(1, 1), b3 + hstep, voffB); PG8_STAGE(PG8_SA(1, 0), a3, voffA);
;             PG8_WAIT_V(8); PG8_WAIT_L(0); PG8_BAR; PG8_MMA(1, 0, At, B0); PG8_MMA(1, 1, At, B1); PG8_BAR; PG8_SCHED;
	s_setprio 0
	s_add_i32 s52, s60, s4
	s_mov_b32 m0, s52
	ds_read_b128 v[180:183], v151 offset:49152
	ds_read_b128 v[184:187], v151 offset:50176
	ds_read_b128 v[188:191], v151 offset:51200
	ds_read_b128 v[192:195], v151 offset:52224
	ds_read_b128 v[196:199], v151 offset:53248
	ds_read_b128 v[200:203], v151 offset:54272
	ds_read_b128 v[204:207], v151 offset:55296
	ds_read_b128 v[208:211], v151 offset:56320
	global_load_lds_dwordx4 v0, s[100:101]
	s_add_i32 m0, s52, 0x2000
	s_add_i32 s52, s61, s4
	global_load_lds_dwordx4 v134, s[100:101]
	s_add_u32 s10, s10, 0x80080
	s_addc_u32 s11, s11, 0
	s_mov_b32 m0, s52
	s_nop 0
	global_load_lds_dwordx4 v0, s[10:11]
	s_add_i32 m0, s52, 0x2000
	s_nop 0
	global_load_lds_dwordx4 v134, s[10:11]
	s_mov_b32 m0, s30
	s_nop 0
	global_load_lds_dwordx4 v130, s[98:99]
	s_mov_b32 m0, s47
	s_nop 0
	global_load_lds_dwordx4 v132, s[98:99]
	s_waitcnt vmcnt(8) lgkmcnt(0)
	s_setprio 1
	s_barrier
	v_mfma_f32_16x16x32_bf16 v[62:65], v[140:143], v[180:183], v[62:65]
	v_mfma_f32_16x16x32_bf16 v[58:61], v[156:159], v[180:183], v[58:61]
	v_mfma_f32_16x16x32_bf16 v[46:49], v[140:143], v[188:191], v[46:49]
	v_mfma_f32_16x16x32_bf16 v[42:45], v[156:159], v[188:191], v[42:45]
	v_mfma_f32_16x16x32_bf16 v[30:33], v[140:143], v[196:199], v[30:33]
	v_mfma_f32_16x16x32_bf16 v[26:29], v[156:159], v[196:199], v[26:29]
	v_mfma_f32_16x16x32_bf16 v[14:17], v[140:143], v[204:207], v[14:17]
	v_mfma_f32_16x16x32_bf16 v[10:13], v[156:159], v[204:207], v[10:13]
	v_mfma_f32_16x16x32_bf16 v[62:65], v[152:155], v[184:187], v[62:65]
	v_mfma_f32_16x16x32_bf16 v[58:61], v[160:163], v[184:187], v[58:61]
	v_mfma_f32_16x16x32_bf16 v[46:49], v[152:155], v[192:195], v[46:49]
	v_mfma_f32_16x16x32_bf16 v[42:45], v[160:163], v[192:195], v[42:45]
	v_mfma_f32_16x16x32_bf16 v[30:33], v[152:155], v[200:203], v[30:33]
	v_mfma_f32_16x16x32_bf16 v[26:29], v[160:163], v[200:203], v[26:29]
	v_mfma_f32_16x16x32_bf16 v[14:17], v[152:155], v[208:211], v[14:17]
	v_mfma_f32_16x16x32_bf16 v[10:13], v[160:163], v[208:211], v[10:13]
	v_mfma_f32_16x16x32_bf16 v[54:57], v[164:167], v[180:183], v[54:57]
	v_mfma_f32_16x16x32_bf16 v[50:53], v[172:175], v[180:183], v[50:53]
	v_mfma_f32_16x16x32_bf16 v[38:41], v[164:167], v[188:191], v[38:41]
	v_mfma_f32_16x16x32_bf16 v[34:37], v[172:175], v[188:191], v[34:37]
	v_mfma_f32_16x16x32_bf16 v[22:25], v[164:167], v[196:199], v[22:25]
	v_mfma_f32_16x16x32_bf16 v[18:21], v[172:175], v[196:199], v[18:21]
	v_mfma_f32_16x16x32_bf16 v[6:9], v[164:167], v[204:207], v[6:9]
	v_mfma_f32_16x16x32_bf16 v[2:5], v[172:175], v[204:207], v[2:5]
	v_mfma_f32_16x16x32_bf16 v[54:57], v[168:171], v[184:187], v[54:57]
	v_mfma_f32_16x16x32_bf16 v[50:53], v[176:179], v[184:187], v[50:53]
	v_mfma_f32_16x16x32_bf16 v[38:41], v[168:171], v[192:195], v[38:41]
	v_mfma_f32_16x16x32_bf16 v[34:37], v[176:179], v[192:195], v[34:37]
	v_mfma_f32_16x16x32_bf16 v[22:25], v[168:171], v[200:203], v[22:25]
	v_mfma_f32_16x16x32_bf16 v[18:21], v[176:179], v[200:203], v[18:21]
	v_mfma_f32_16x16x32_bf16 v[6:9], v[168:171], v[208:211], v[6:9]
	v_mfma_f32_16x16x32_bf16 v[2:5], v[176:179], v[208:211], v[2:5]
	s_barrier
	s_setprio 0
	s_add_i32 s59, s59, 2
	s_add_u32 s50, s50, 0x100
	s_addc_u32 s51, s51, 0
	s_add_u32 s57, s57, 0x100
	s_addc_u32 s58, s58, 0

; __device__ __forceinline__ unsigned cvt_pk_bf16(float lo, float hi) { unsigned r; asm volatile("v_cvt_pk_bf16_f32 %0, %1, %2" : "=v"(r) : "v"(lo), "v"(hi)); return r; }
; #define PG8_BAR __builtin_amdgcn_s_barrier()
;     __device__ __forceinline__ void operator()(const f32x4 (&acc)[2][2][4][2], const Unit& u, int wr, int wc, int fr, int fq) const {
;     ...
;             for (int m = 0; m < 4; ++m) { bf16_t* rowp = Ob + (size_t)(row0 + ai * HALF + m * 16) * ld + col0;
;                 float rs = 1.f; if (ss) rs = __builtin_amdgcn_rsqf((float)ss[row0 + ai * HALF + m * 16] * (1.f / (2048.f * 262144.f)) + 1e-6f);
; #pragma unroll
;                 for (int bj = 0; bj < 2; ++bj) { const f32x4 v0 = acc[ai][bj][m][0] * rs, v1 = acc[ai][bj][m][1] * rs;
;                     u32x4 w; w.x = cvt_pk_bf16(v0[0], v0[1]); w.y = cvt_pk_bf16(v0[2], v0[3]); w.z = cvt_pk_bf16(v1[0], v1[1]); w.w = cvt_pk_bf16(v1[2], v1[3]);
;                     *(u32x4*)(rowp + bj * HALF) = w; } }
; template <class Epi, class Sched, bool ALIGN_EPI = false, bool SP2 = false>
; __device__ __forceinline__ void gemm_phase(PG8_LAS unsigned char* lds, const Gemm g, const Sched& S, const Epi& E) {
;     ...
;         if constexpr (!Epi::AFTER_DRAIN) { E(acc, cur, wr, wc, fr, fq); S.done(cur); }
;         if (!has_next) break;
; #pragma unroll
;         for (int a = 0; a < 2; ++a)
; #pragma unroll
;             for (int b = 0; b < 2; ++b)
; #pragma unroll
;                 for (int m = 0; m < 4; ++m)
; #pragma unroll
;                     for (int n = 0; n < 2; ++n) acc[a][b][m][n] = (f32x4){0.f, 0.f, 0.f, 0.f};
;         cur = nxt; cA = nA; cB = nB; ++ui;
;         if constexpr (ALIGN_EPI) { if (wr == 1) PG8_BAR; }
.LBB0_578:
	s_nop 0
	v_add_u32_e32 v18, 0xb0, v140
	v_mad_i64_i32 v[18:19], s[10:11], s10, v18, 0
	v_lshl_add_u64 v[18:19], v[18:19], 1, v[144:145]
	v_pk_mul_f32 v[16:17], v[16:17], v[34:35] op_sel_hi:[1,0]
	v_pk_mul_f32 v[14:15], v[14:15], v[34:35] op_sel_hi:[1,0]
	v_pk_mul_f32 v[20:21], v[12:13], v[34:35] op_sel_hi:[1,0]
	v_pk_mul_f32 v[12:13], v[10:11], v[34:35] op_sel_hi:[1,0]
	v_cvt_pk_bf16_f32 v10, v14, v15
	v_cvt_pk_bf16_f32 v11, v16, v17
	s_andn2_b64 vcc, exec, s[40:41]
	v_cvt_pk_bf16_f32 v12, v12, v13
	v_cvt_pk_bf16_f32 v13, v20, v21
	global_store_dwordx4 v[18:19], v[10:13], off
	s_mov_b64 s[10:11], -1
	v_pk_mul_f32 v[8:9], v[8:9], v[34:35] op_sel_hi:[1,0]
	v_pk_mul_f32 v[10:11], v[4:5], v[34:35] op_sel_hi:[1,0]
	v_pk_mul_f32 v[4:5], v[2:3], v[34:35] op_sel_hi:[1,0]
	v_pk_mul_f32 v[6:7], v[6:7], v[34:35] op_sel_hi:[1,0]
	s_nop 0
	v_cvt_pk_bf16_f32 v2, v6, v7
	v_cvt_pk_bf16_f32 v3, v8, v9
	v_cvt_pk_bf16_f32 v4, v4, v5
	v_cvt_pk_bf16_f32 v5, v10, v11
	global_store_dwordx4 v[18:19], v[2:5], off offset:256
	s_cbranch_vccnz .LBB0_555
	s_andn2_b64 vcc, exec, s[8:9]
	s_cbranch_vccnz .LBB0_554
	s_branch .LBB0_554
